# MLA loop QK^T block: K-fragment reads issued one MFMA earlier (right after the MFMA that last used their registers), per-MFMA counted waits
# speedup vs baseline: 1.0043x; 1.0009x over previous
; __device__ __forceinline__ void finishSM(f32x16& p0, f32x16& p1, float alpha, float& l_reg, bf16x8& pa0, bf16x8& pa1, bf16x8& pa2, bf16x8& pa3) {
; #pragma unroll
;     for (int r = 0; r < 16; ++r) p1[r] = __builtin_amdgcn_exp2f(p1[r]);
;     float ps = 0;
; #pragma unroll
;     for (int r = 0; r < 16; ++r) ps += p0[r];
; #pragma unroll
;     for (int r = 0; r < 16; ++r) ps += p1[r];
;     { auto rr = __builtin_amdgcn_permlane32_swap(__float_as_uint(ps), __float_as_uint(ps), false, false);
;       ps = __uint_as_float(rr[0]) + __uint_as_float(rr[1]); }
;     l_reg = l_reg * alpha + ps;
.LBB0_219:
	ds_read_b128 v[64:67], v184 offset:57344
	ds_read_b128 v[68:71], v216 offset:12288
	ds_read_b128 v[222:225], v192 offset:57344
	ds_read_b128 v[226:229], v208 offset:12288
	v_exp_f32_e32 v207, v130
	v_add_f32_e32 v130, 0, v219
	s_waitcnt lgkmcnt(3)
	v_mfma_f32_32x32x16_bf16 v[80:95], v[64:67], v[126:129], 0
	v_add_f32_e32 v130, v221, v130
	v_add_f32_e32 v130, v157, v130
	v_add_f32_e32 v130, v220, v130
	v_add_f32_e32 v130, v156, v130
	v_add_f32_e32 v130, v218, v130
	v_add_f32_e32 v130, v154, v130
	v_add_f32_e32 v130, v155, v130
	s_waitcnt lgkmcnt(2)
	v_mfma_f32_32x32x16_bf16 v[64:79], v[68:71], v[126:129], 0
	v_add_f32_e32 v130, v151, v130
	v_add_f32_e32 v130, v153, v130
	v_add_f32_e32 v130, v150, v130
	v_add_f32_e32 v130, v152, v130
	v_exp_f32_e32 v142, v142
	v_add_f32_e32 v130, v147, v130
	v_exp_f32_e32 v143, v143
	s_waitcnt lgkmcnt(1)
	v_mfma_f32_32x32x16_bf16 v[80:95], v[222:225], v[122:125], v[80:95]
	v_add_f32_e32 v130, v149, v130
	v_exp_f32_e32 v140, v140
	v_add_f32_e32 v130, v146, v130
	v_exp_f32_e32 v141, v141
	v_add_f32_e32 v130, v148, v130
	v_exp_f32_e32 v134, v134
	v_add_f32_e32 v130, v142, v130
	s_waitcnt lgkmcnt(0)
	v_mfma_f32_32x32x16_bf16 v[64:79], v[226:229], v[122:125], v[64:79]
	ds_read_b128 v[222:225], v190 offset:57344
	ds_read_b128 v[226:229], v206 offset:12288
	v_exp_f32_e32 v135, v135
	v_add_f32_e32 v130, v143, v130
	v_exp_f32_e32 v191, v132
	v_add_f32_e32 v130, v140, v130
	v_exp_f32_e32 v205, v133
	v_add_f32_e32 v130, v141, v130
	s_waitcnt lgkmcnt(1)
	v_mfma_f32_32x32x16_bf16 v[80:95], v[222:225], v[118:121], v[80:95]
	v_add_f32_e32 v130, v134, v130
	v_exp_f32_e32 v210, v131
	v_add_f32_e32 v130, v135, v130
	v_exp_f32_e32 v144, v144
	v_add_f32_e32 v130, v191, v130
	v_exp_f32_e32 v145, v145
	v_add_f32_e32 v130, v205, v130
	s_waitcnt lgkmcnt(0)
	v_mfma_f32_32x32x16_bf16 v[64:79], v[226:229], v[118:121], v[64:79]
	ds_read_b128 v[222:225], v173 offset:57344
	ds_read_b128 v[226:229], v202 offset:12288
	v_exp_f32_e32 v138, v138
	v_add_f32_e32 v130, v207, v130
	v_exp_f32_e32 v139, v139
	v_add_f32_e32 v130, v210, v130
	v_exp_f32_e32 v136, v136
	v_add_f32_e32 v130, v144, v130
	s_waitcnt lgkmcnt(1)
	v_mfma_f32_32x32x16_bf16 v[80:95], v[222:225], v[114:117], v[80:95]
	ds_read_b128 v[222:225], v184 offset:57472
	v_exp_f32_e32 v137, v137
	v_add_f32_e32 v130, v145, v130
	v_add_f32_e32 v130, v138, v130
	v_add_f32_e32 v130, v139, v130
	v_add_f32_e32 v130, v136, v130
	s_waitcnt lgkmcnt(1)
	v_mfma_f32_32x32x16_bf16 v[64:79], v[226:229], v[114:117], v[64:79]
	ds_read_b128 v[226:229], v216 offset:12416
	s_waitcnt lgkmcnt(1)
	v_mfma_f32_32x32x16_bf16 v[80:95], v[222:225], v[110:113], v[80:95]
	ds_read_b128 v[222:225], v192 offset:57472
	s_waitcnt lgkmcnt(1)
	v_mfma_f32_32x32x16_bf16 v[64:79], v[226:229], v[110:113], v[64:79]
	ds_read_b128 v[226:229], v208 offset:12416
	s_waitcnt lgkmcnt(1)
	v_mfma_f32_32x32x16_bf16 v[80:95], v[222:225], v[106:109], v[80:95]
	ds_read_b128 v[222:225], v190 offset:57472
	s_waitcnt lgkmcnt(1)
	v_mfma_f32_32x32x16_bf16 v[64:79], v[226:229], v[106:109], v[64:79]
	ds_read_b128 v[226:229], v206 offset:12416
	s_waitcnt lgkmcnt(1)
	v_mfma_f32_32x32x16_bf16 v[80:95], v[222:225], v[102:105], v[80:95]
	ds_read_b128 v[222:225], v173 offset:57472
	s_waitcnt lgkmcnt(1)
	v_mfma_f32_32x32x16_bf16 v[64:79], v[226:229], v[102:105], v[64:79]
	ds_read_b128 v[226:229], v202 offset:12416
	s_waitcnt lgkmcnt(1)
	v_mfma_f32_32x32x16_bf16 v[80:95], v[222:225], v[98:101], v[80:95]
	s_waitcnt lgkmcnt(0)
	v_mfma_f32_32x32x16_bf16 v[64:79], v[226:229], v[98:101], v[64:79]
	ds_read_b128 v[222:225], v184 offset:57600
	ds_read_b128 v[226:229], v216 offset:12544
	ds_read_b128 v[230:233], v181
	s_waitcnt lgkmcnt(0)
	v_mfma_f32_32x32x16_bf16 v[80:95], v[222:225], v[230:233], v[80:95]
	v_mfma_f32_32x32x16_bf16 v[64:79], v[226:229], v[230:233], v[64:79]
	ds_read_b128 v[222:225], v192 offset:57600
	ds_read_b128 v[226:229], v208 offset:12544
	ds_read_b128 v[230:233], v181 offset:8192
	s_waitcnt lgkmcnt(0)
	v_mfma_f32_32x32x16_bf16 v[80:95], v[222:225], v[230:233], v[80:95]
	v_mfma_f32_32x32x16_bf16 v[64:79], v[226:229], v[230:233], v[64:79]
	ds_read_b128 v[222:225], v190 offset:57600
	ds_read_b128 v[226:229], v206 offset:12544
	ds_read_b128 v[230:233], v181 offset:16384
	s_waitcnt lgkmcnt(0)
	v_mfma_f32_32x32x16_bf16 v[80:95], v[222:225], v[230:233], v[80:95]
	v_mfma_f32_32x32x16_bf16 v[64:79], v[226:229], v[230:233], v[64:79]
	ds_read_b128 v[222:225], v173 offset:57600
	ds_read_b128 v[226:229], v202 offset:12544
	ds_read_b128 v[230:233], v181 offset:24576
	s_waitcnt lgkmcnt(0)
; template <int D0> __device__ __forceinline__ void pv_one(f32x16& od, int vb, bf16x8 pa0, bf16x8 pa1, bf16x8 pa2, bf16x8 pa3) {
;     const s16x4 l0 = tr_read<v_rd_off(D0, 0, 0)>(vb), h0 = tr_read<v_rd_off(D0, 0, 1)>(vb), l1 = tr_read<v_rd_off(D0, 1, 0)>(vb), h1 = tr_read<v_rd_off(D0, 1, 1)>(vb);
;     const s16x4 l2 = tr_read<v_rd_off(D0, 2, 0)>(vb), h2 = tr_read<v_rd_off(D0, 2, 1)>(vb), l3 = tr_read<v_rd_off(D0, 3, 0)>(vb), h3 = tr_read<v_rd_off(D0, 3, 1)>(vb);
;     asm volatile("s_waitcnt lgkmcnt(0)" ::: "memory"); SBAR();
;     ...
;     od = __builtin_amdgcn_mfma_f32_32x32x16_bf16(pa0, PK(l0, h0), od, 0, 0, 0);
;     od = __builtin_amdgcn_mfma_f32_32x32x16_bf16(pa1, PK(l1, h1), od, 0, 0, 0);
;     od = __builtin_amdgcn_mfma_f32_32x32x16_bf16(pa2, PK(l2, h2), od, 0, 0, 0);
;     od = __builtin_amdgcn_mfma_f32_32x32x16_bf16(pa3, PK(l3, h3), od, 0, 0, 0);
;     ...
; }
; __device__ __forceinline__ void pv_d0(f32x16* o, int vb, bf16x8 pa0, bf16x8 pa1, bf16x8 pa2, bf16x8 pa3) {
;     pv_one<0>(o[0], vb, pa0, pa1, pa2, pa3); pv_one<1>(o[1], vb, pa0, pa1, pa2, pa3); pv_one<2>(o[2], vb, pa0, pa1, pa2, pa3); pv_one<3>(o[3], vb, pa0, pa1, pa2, pa3);
; }
; __device__ __forceinline__ void partialSM(f32x16& p0, f32x16& p1, float& m_reg, float& mn, float& alpha, const float C, const float thr) {
;     float pmax = p0[0];
; #pragma unroll
;     for (int r = 1; r < 16; ++r) pmax = fmaxf(pmax, p0[r]);
; #pragma unroll
;     for (int r = 0; r < 16; ++r) pmax = fmaxf(pmax, p1[r]);
;     { auto rr = __builtin_amdgcn_permlane32_swap(__float_as_uint(pmax), __float_as_uint(pmax), false, false);
;       pmax = fmaxf(__uint_as_float(rr[0]), __uint_as_float(rr[1])); }
;     if (__builtin_expect(__all(pmax - m_reg <= thr), 1)) { mn = m_reg; alpha = 1.f; }
;     else { mn = fmaxf(m_reg, pmax); alpha = __builtin_amdgcn_exp2f((m_reg - mn) * C); m_reg = mn; }
;     const float mnC = -mn * C;
; #pragma unroll
;     for (int r = 0; r < 16; ++r) p0[r] = fmaf(p0[r], C, mnC);
; #pragma unroll
;     for (int r = 0; r < 16; ++r) p1[r] = fmaf(p1[r], C, mnC);
; #pragma unroll
;     for (int r = 0; r < 16; ++r) p0[r] = __builtin_amdgcn_exp2f(p0[r]);
; }
; __device__ __forceinline__ void finishSM(f32x16& p0, f32x16& p1, float alpha, float& l_reg, bf16x8& pa0, bf16x8& pa1, bf16x8& pa2, bf16x8& pa3) {
; #pragma unroll
;     for (int r = 0; r < 16; ++r) p1[r] = __builtin_amdgcn_exp2f(p1[r]);
;     float ps = 0;
	v_mfma_f32_32x32x16_bf16 v[80:95], v[222:225], v[230:233], v[80:95]
	v_add_f32_e32 v222, v137, v130
	v_mov_b32_e32 v223, v222
	v_cvt_pk_bf16_f32 v130, v219, v221
	v_cvt_pk_bf16_f32 v131, v157, v220
	v_cvt_pk_bf16_f32 v132, v156, v218
	v_cvt_pk_bf16_f32 v133, v154, v155
	v_cvt_pk_bf16_f32 v154, v151, v153
	v_mfma_f32_32x32x16_bf16 v[64:79], v[226:229], v[230:233], v[64:79]
	v_cvt_pk_bf16_f32 v155, v150, v152
	v_cvt_pk_bf16_f32 v156, v147, v149
	v_cvt_pk_bf16_f32 v157, v146, v148
	v_cvt_pk_bf16_f32 v218, v142, v143
	v_cvt_pk_bf16_f32 v219, v140, v141
	v_cvt_pk_bf16_f32 v220, v134, v135
	v_cvt_pk_bf16_f32 v221, v191, v205
	v_cvt_pk_bf16_f32 v224, v207, v210
	v_cvt_pk_bf16_f32 v225, v144, v145
	v_cvt_pk_bf16_f32 v226, v138, v139
	v_cvt_pk_bf16_f32 v227, v136, v137
	s_nop 0
	v_permlane32_swap_b32_e32 v222, v223
	v_permlane32_swap_b32_e32 v130, v132
	v_permlane32_swap_b32_e32 v225, v227
	v_permlane32_swap_b32_e32 v131, v133
	v_permlane32_swap_b32_e32 v154, v156
	v_permlane32_swap_b32_e32 v155, v157
	v_permlane32_swap_b32_e32 v218, v220
	v_permlane32_swap_b32_e32 v219, v221
	v_permlane32_swap_b32_e32 v224, v226
	s_cmp_lt_u32 s69, s68
	s_cselect_b32 s14, 0, s68
	s_cselect_b32 s15, s25, s28
	s_lshl_b32 s14, s14, 6
	s_sub_i32 s14, s15, s14
	s_add_i32 s14, s37, s14
	s_ashr_i32 s15, s14, 31
	v_lshl_add_u64 v[134:135], s[14:15], 0, v[174:175]
	v_lshl_add_u64 v[136:137], v[176:177], 0, s[14:15]
	v_lshlrev_b64 v[134:135], 12, v[134:135]
	v_lshlrev_b64 v[136:137], 12, v[136:137]
	v_lshl_add_u64 v[134:135], v[178:179], 0, v[134:135]
	v_lshl_add_u64 v[138:139], v[178:179], 0, v[136:137]
	v_mad_i64_i32 v[142:143], s[20:21], v164, s14, 0
	v_mad_i64_i32 v[146:147], s[20:21], v168, s14, 0
	v_mad_i64_i32 v[150:151], s[14:15], v172, s14, 0
	global_load_dwordx4 v[134:137], v[134:135], off offset:256
	s_nop 0
	global_load_dwordx4 v[138:141], v[138:139], off offset:256
	v_lshl_add_u64 v[142:143], v[142:143], 1, v[162:163]
	v_lshl_add_u64 v[146:147], v[146:147], 1, v[166:167]
	v_lshl_add_u64 v[150:151], v[150:151], 1, v[170:171]
	global_load_dwordx4 v[142:145], v[142:143], off
	s_nop 0
	global_load_dwordx4 v[146:149], v[146:147], off
	s_nop 0
	global_load_dwordx4 v[150:153], v[150:151], off
	ds_read_b64_tr_b16 v[228:229], v200 offset:0
	ds_read_b64_tr_b16 v[230:231], v200 offset:0x800
	ds_read_b64_tr_b16 v[232:233], v200 offset:0x1000
	ds_read_b64_tr_b16 v[234:235], v200 offset:0x1800
	ds_read_b64_tr_b16 v[236:237], v200 offset:0x2000
	ds_read_b64_tr_b16 v[238:239], v200 offset:0x2800
	ds_read_b64_tr_b16 v[240:241], v200 offset:0x3000
	ds_read_b64_tr_b16 v[242:243], v200 offset:0x3800
	s_waitcnt lgkmcnt(0)
	s_nop 0
	v_mfma_f32_32x32x16_bf16 v[48:63], v[130:133], v[228:231], v[48:63]
	ds_read_b64_tr_b16 v[228:229], v200 offset:0x200
	ds_read_b64_tr_b16 v[230:231], v200 offset:0xa00
	v_mfma_f32_32x32x16_bf16 v[48:63], v[154:157], v[232:235], v[48:63]
	ds_read_b64_tr_b16 v[232:233], v200 offset:0x1200
	ds_read_b64_tr_b16 v[234:235], v200 offset:0x1a00
	v_mfma_f32_32x32x16_bf16 v[48:63], v[218:221], v[236:239], v[48:63]
	ds_read_b64_tr_b16 v[236:237], v200 offset:0x2200
	ds_read_b64_tr_b16 v[238:239], v200 offset:0x2a00
	v_mfma_f32_32x32x16_bf16 v[48:63], v[224:227], v[240:243], v[48:63]
	ds_read_b64_tr_b16 v[240:241], v200 offset:0x3200
	ds_read_b64_tr_b16 v[242:243], v200 offset:0x3a00
	s_waitcnt lgkmcnt(6)
	v_mfma_f32_32x32x16_bf16 v[32:47], v[130:133], v[228:231], v[32:47]
	ds_read_b64_tr_b16 v[228:229], v200 offset:0x400
	ds_read_b64_tr_b16 v[230:231], v200 offset:0xc00
	s_waitcnt lgkmcnt(6)
	v_mfma_f32_32x32x16_bf16 v[32:47], v[154:157], v[232:235], v[32:47]
	ds_read_b64_tr_b16 v[232:233], v200 offset:0x1400
	ds_read_b64_tr_b16 v[234:235], v200 offset:0x1c00
	s_waitcnt lgkmcnt(6)
	v_mfma_f32_32x32x16_bf16 v[32:47], v[218:221], v[236:239], v[32:47]
	ds_read_b64_tr_b16 v[236:237], v200 offset:0x2400
	ds_read_b64_tr_b16 v[238:239], v200 offset:0x2c00
	s_waitcnt lgkmcnt(6)
	v_mfma_f32_32x32x16_bf16 v[32:47], v[224:227], v[240:243], v[32:47]
	ds_read_b64_tr_b16 v[240:241], v200 offset:0x3400
	ds_read_b64_tr_b16 v[242:243], v200 offset:0x3c00
	s_waitcnt lgkmcnt(6)
	v_mfma_f32_32x32x16_bf16 v[16:31], v[130:133], v[228:231], v[16:31]
	ds_read_b64_tr_b16 v[228:229], v200 offset:0x600
	ds_read_b64_tr_b16 v[230:231], v200 offset:0xe00
	s_waitcnt lgkmcnt(6)
	v_mfma_f32_32x32x16_bf16 v[16:31], v[154:157], v[232:235], v[16:31]
	ds_read_b64_tr_b16 v[232:233], v200 offset:0x1600
	ds_read_b64_tr_b16 v[234:235], v200 offset:0x1e00
	s_waitcnt lgkmcnt(6)
	v_mfma_f32_32x32x16_bf16 v[16:31], v[218:221], v[236:239], v[16:31]
	ds_read_b64_tr_b16 v[236:237], v200 offset:0x2600
	ds_read_b64_tr_b16 v[238:239], v200 offset:0x2e00
	s_waitcnt lgkmcnt(6)
	v_mfma_f32_32x32x16_bf16 v[16:31], v[224:227], v[240:243], v[16:31]
	ds_read_b64_tr_b16 v[240:241], v200 offset:0x3600
	ds_read_b64_tr_b16 v[242:243], v200 offset:0x3e00
	s_waitcnt lgkmcnt(6)
	v_mfma_f32_32x32x16_bf16 v[0:15], v[130:133], v[228:231], v[0:15]
	v_max_f32_e32 v130, v81, v81
	v_max_f32_e32 v131, v80, v80
	v_max_f32_e32 v130, v131, v130
	v_max3_f32 v130, v130, v82, v83
	v_max3_f32 v130, v130, v84, v85
	v_max3_f32 v130, v130, v86, v87
	v_max3_f32 v130, v130, v88, v89
	v_max3_f32 v130, v130, v90, v91
	v_max3_f32 v130, v130, v92, v93
	s_waitcnt lgkmcnt(4)
	v_mfma_f32_32x32x16_bf16 v[0:15], v[154:157], v[232:235], v[0:15]
	v_max3_f32 v130, v130, v94, v95
	v_max3_f32 v130, v130, v64, v65
	v_max3_f32 v130, v130, v66, v67
	v_max3_f32 v130, v130, v68, v69
	v_max3_f32 v130, v130, v70, v71
	v_max3_f32 v130, v130, v72, v73
	v_max3_f32 v130, v130, v74, v75
	v_max3_f32 v130, v130, v76, v77
	s_waitcnt lgkmcnt(2)
	v_mfma_f32_32x32x16_bf16 v[0:15], v[218:221], v[236:239], v[0:15]
	v_max3_f32 v130, v130, v78, v79
	v_mov_b32_e32 v131, v130
	s_nop 1
	v_permlane32_swap_b32_e32 v130, v131
	v_max_f32_e32 v131, v131, v131
	v_max_f32_e32 v130, v130, v130
	v_max_f32_e32 v130, v130, v131
	v_sub_f32_e32 v131, v130, v204
	v_cmp_ge_f32_e32 vcc, s72, v131
	v_max_f32_e32 v131, v204, v204
	v_max_f32_e32 v130, v131, v130
	s_waitcnt lgkmcnt(0)
	v_mfma_f32_32x32x16_bf16 v[0:15], v[224:227], v[240:243], v[0:15]
	v_sub_f32_e32 v131, v204, v130
	v_mul_f32_e32 v131, 0x3dd53b94, v131
	v_exp_f32_e32 v131, v131
	s_cmp_eq_u64 vcc, exec
	s_cselect_b64 s[14:15], -1, 0
	v_cndmask_b32_e64 v225, v131, 1.0, s[14:15]
	v_cmp_gt_f32_e32 vcc, 1.0, v225
	s_barrier
; __device__ __forceinline__ void partialSM(f32x16& p0, f32x16& p1, float& m_reg, float& mn, float& alpha, const float C, const float thr) {
;     ...
;     else { mn = fmaxf(m_reg, pmax); alpha = __builtin_amdgcn_exp2f((m_reg - mn) * C); m_reg = mn; }
;     const float mnC = -mn * C;
; #pragma unroll
;     for (int r = 0; r < 16; ++r) p0[r] = fmaf(p0[r], C, mnC);
; #pragma unroll
;     for (int r = 0; r < 16; ++r) p1[r] = fmaf(p1[r], C, mnC);
; #pragma unroll
;     for (int r = 0; r < 16; ++r) p0[r] = __builtin_amdgcn_exp2f(p0[r]);
; }
; __device__ __forceinline__ void finishSM(f32x16& p0, f32x16& p1, float alpha, float& l_reg, bf16x8& pa0, bf16x8& pa1, bf16x8& pa2, bf16x8& pa3) {
; #pragma unroll
;     for (int r = 0; r < 16; ++r) p1[r] = __builtin_amdgcn_exp2f(p1[r]);
	s_waitcnt vmcnt(4)
	ds_write_b128 v186, v[134:137]
	s_waitcnt vmcnt(3)
	ds_write_b128 v188, v[138:141]
	s_waitcnt vmcnt(2)
	ds_write_b128 v194, v[142:145] offset:32768
	s_waitcnt vmcnt(1)
	ds_write_b128 v196, v[146:149] offset:32768
	s_waitcnt vmcnt(0)
	ds_write_b128 v198, v[150:153] offset:32768
	s_cbranch_vccz .LBB0_223
	s_and_saveexec_b64 s[20:21], s[12:13]
	ds_write_b32 v165, v225 offset:128
	s_or_b64 exec, exec, s[20:21]
	s_waitcnt lgkmcnt(0)
	v_add_u32_e32 v131, v161, v96
	ds_read_b128 v[132:135], v131 offset:224
	ds_read_b128 v[136:139], v131 offset:192
	ds_read_b128 v[140:143], v131 offset:160
	ds_read_b128 v[144:147], v131 offset:128
	s_waitcnt lgkmcnt(3)
	v_pk_mul_f32 v[60:61], v[60:61], v[132:133]
	s_waitcnt lgkmcnt(2)
	v_pk_mul_f32 v[56:57], v[56:57], v[136:137]
	s_waitcnt lgkmcnt(1)
	v_pk_mul_f32 v[52:53], v[52:53], v[140:141]
	v_pk_mul_f32 v[62:63], v[62:63], v[134:135]
	v_pk_mul_f32 v[58:59], v[58:59], v[138:139]
	v_pk_mul_f32 v[54:55], v[54:55], v[142:143]
	s_waitcnt lgkmcnt(0)
	v_pk_mul_f32 v[50:51], v[50:51], v[146:147]
	v_pk_mul_f32 v[48:49], v[48:49], v[144:145]
	v_pk_mul_f32 v[44:45], v[44:45], v[132:133]
	v_pk_mul_f32 v[40:41], v[40:41], v[136:137]
	v_pk_mul_f32 v[36:37], v[36:37], v[140:141]
	v_pk_mul_f32 v[46:47], v[46:47], v[134:135]
	v_pk_mul_f32 v[42:43], v[42:43], v[138:139]
	v_pk_mul_f32 v[38:39], v[38:39], v[142:143]
	v_pk_mul_f32 v[34:35], v[34:35], v[146:147]
	v_pk_mul_f32 v[32:33], v[32:33], v[144:145]
	v_pk_mul_f32 v[28:29], v[28:29], v[132:133]
	v_pk_mul_f32 v[24:25], v[24:25], v[136:137]
	v_pk_mul_f32 v[20:21], v[20:21], v[140:141]
	v_pk_mul_f32 v[30:31], v[30:31], v[134:135]
	v_pk_mul_f32 v[26:27], v[26:27], v[138:139]
	v_pk_mul_f32 v[22:23], v[22:23], v[142:143]
	v_pk_mul_f32 v[18:19], v[18:19], v[146:147]
	v_pk_mul_f32 v[16:17], v[16:17], v[144:145]
	v_pk_mul_f32 v[12:13], v[12:13], v[132:133]
	v_pk_mul_f32 v[8:9], v[8:9], v[136:137]
	v_pk_mul_f32 v[4:5], v[4:5], v[140:141]
	v_pk_mul_f32 v[14:15], v[14:15], v[134:135]
	v_pk_mul_f32 v[10:11], v[10:11], v[138:139]
	v_pk_mul_f32 v[6:7], v[6:7], v[142:143]
	v_pk_mul_f32 v[2:3], v[2:3], v[146:147]
	v_pk_mul_f32 v[0:1], v[0:1], v[144:145]
.LBB0_223:
	v_cndmask_b32_e64 v204, v130, v204, s[14:15]
	v_mul_f32_e32 v138, 0xbdd53b94, v204
	v_fmamk_f32 v80, v80, 0x3dd53b94, v138
	v_fmamk_f32 v140, v70, 0x3dd53b94, v138
	v_fmamk_f32 v70, v87, 0x3dd53b94, v138
	v_exp_f32_e32 v130, v80
	v_exp_f32_e32 v224, v70
	v_fmamk_f32 v82, v82, 0x3dd53b94, v138
	v_fmamk_f32 v84, v84, 0x3dd53b94, v138
	v_fmamk_f32 v86, v86, 0x3dd53b94, v138
	v_fmamk_f32 v88, v88, 0x3dd53b94, v138
	v_fmamk_f32 v90, v90, 0x3dd53b94, v138
	v_fmamk_f32 v92, v92, 0x3dd53b94, v138
	v_fmamk_f32 v94, v94, 0x3dd53b94, v138
	v_fmamk_f32 v145, v64, 0x3dd53b94, v138
	v_fmamk_f32 v144, v66, 0x3dd53b94, v138
	v_fmamk_f32 v143, v68, 0x3dd53b94, v138
	v_fmamk_f32 v139, v72, 0x3dd53b94, v138
	v_fmamk_f32 v146, v74, 0x3dd53b94, v138
	v_fmamk_f32 v142, v76, 0x3dd53b94, v138
	v_fmamk_f32 v141, v78, 0x3dd53b94, v138
	v_fmamk_f32 v64, v81, 0x3dd53b94, v138
	v_fmamk_f32 v66, v83, 0x3dd53b94, v138
	v_fmamk_f32 v68, v85, 0x3dd53b94, v138
	v_fmamk_f32 v72, v89, 0x3dd53b94, v138
	v_fmamk_f32 v74, v91, 0x3dd53b94, v138
	v_fmamk_f32 v76, v93, 0x3dd53b94, v138
	v_fmamk_f32 v78, v95, 0x3dd53b94, v138
	v_exp_f32_e32 v131, v82
	v_exp_f32_e32 v132, v84
	v_exp_f32_e32 v133, v86
	v_exp_f32_e32 v137, v88
	v_exp_f32_e32 v136, v90
	v_exp_f32_e32 v135, v92
	v_exp_f32_e32 v134, v94
	v_fmamk_f32 v147, v65, 0x3dd53b94, v138
	v_fmamk_f32 v156, v67, 0x3dd53b94, v138
	v_fmamk_f32 v157, v69, 0x3dd53b94, v138
	v_fmamk_f32 v191, v71, 0x3dd53b94, v138
	v_fmamk_f32 v205, v73, 0x3dd53b94, v138
	v_fmamk_f32 v207, v75, 0x3dd53b94, v138
	v_fmamk_f32 v210, v77, 0x3dd53b94, v138
	v_fmac_f32_e32 v138, 0x3dd53b94, v79
	v_exp_f32_e32 v211, v64
	v_exp_f32_e32 v212, v66
	v_exp_f32_e32 v213, v68
	v_exp_f32_e32 v228, v72
	v_exp_f32_e32 v229, v74
	v_exp_f32_e32 v230, v76
	v_exp_f32_e32 v231, v78
	s_waitcnt lgkmcnt(0)
	s_barrier
	ds_read_b128 v[64:67], v184 offset:32768
	ds_read_b128 v[68:71], v184 offset:45056
	ds_read_b128 v[148:151], v192 offset:32768
	ds_read_b128 v[152:155], v192 offset:45056
	v_exp_f32_e32 v145, v145
	v_exp_f32_e32 v147, v147
	s_waitcnt lgkmcnt(3)
	v_mfma_f32_32x32x16_bf16 v[80:95], v[64:67], v[126:129], 0
	v_exp_f32_e32 v144, v144
	v_exp_f32_e32 v143, v143
	v_exp_f32_e32 v140, v140
	v_exp_f32_e32 v139, v139
	v_exp_f32_e32 v146, v146
	v_exp_f32_e32 v142, v142
	v_exp_f32_e32 v141, v141
	s_waitcnt lgkmcnt(2)
	v_mfma_f32_32x32x16_bf16 v[64:79], v[68:71], v[126:129], 0
	v_exp_f32_e32 v138, v138
	s_waitcnt lgkmcnt(0)
	v_mfma_f32_32x32x16_bf16 v[64:79], v[152:155], v[122:125], v[64:79]
	ds_read_b128 v[152:155], v190 offset:45056
	v_mfma_f32_32x32x16_bf16 v[80:95], v[148:151], v[122:125], v[80:95]
	ds_read_b128 v[148:151], v190 offset:32768
	s_waitcnt lgkmcnt(1)
	v_mfma_f32_32x32x16_bf16 v[64:79], v[152:155], v[118:121], v[64:79]
	ds_read_b128 v[152:155], v173 offset:45056
	s_waitcnt lgkmcnt(1)
	v_mfma_f32_32x32x16_bf16 v[80:95], v[148:151], v[118:121], v[80:95]
	ds_read_b128 v[148:151], v173 offset:32768
	s_waitcnt lgkmcnt(1)
	v_mfma_f32_32x32x16_bf16 v[64:79], v[152:155], v[114:117], v[64:79]
	ds_read_b128 v[152:155], v184 offset:45184
	s_waitcnt lgkmcnt(1)
	v_mfma_f32_32x32x16_bf16 v[80:95], v[148:151], v[114:117], v[80:95]
	ds_read_b128 v[148:151], v184 offset:32896
	s_waitcnt lgkmcnt(1)
	v_mfma_f32_32x32x16_bf16 v[64:79], v[152:155], v[110:113], v[64:79]
	ds_read_b128 v[152:155], v192 offset:45184
	s_waitcnt lgkmcnt(1)
	v_mfma_f32_32x32x16_bf16 v[80:95], v[148:151], v[110:113], v[80:95]
	ds_read_b128 v[148:151], v192 offset:32896
	s_waitcnt lgkmcnt(1)
; __device__ __forceinline__ void finishSM(f32x16& p0, f32x16& p1, float alpha, float& l_reg, bf16x8& pa0, bf16x8& pa1, bf16x8& pa2, bf16x8& pa3) {
; #pragma unroll
;     for (int r = 0; r < 16; ++r) p1[r] = __builtin_amdgcn_exp2f(p1[r]);
;     float ps = 0;
; #pragma unroll
;     for (int r = 0; r < 16; ++r) ps += p0[r];
; #pragma unroll
;     for (int r = 0; r < 16; ++r) ps += p1[r];
;     { auto rr = __builtin_amdgcn_permlane32_swap(__float_as_uint(ps), __float_as_uint(ps), false, false);
;       ps = __uint_as_float(rr[0]) + __uint_as_float(rr[1]); }
;     l_reg = l_reg * alpha + ps;
;     ...
;     PK4(p0, 0, pa0); PK4(p0, 8, pa1); PK4(p1, 0, pa2); PK4(p1, 8, pa3);
	v_mfma_f32_32x32x16_bf16 v[64:79], v[152:155], v[106:109], v[64:79]
	ds_read_b128 v[152:155], v190 offset:45184
	s_waitcnt lgkmcnt(1)
	v_mfma_f32_32x32x16_bf16 v[80:95], v[148:151], v[106:109], v[80:95]
	ds_read_b128 v[148:151], v190 offset:32896
	s_waitcnt lgkmcnt(1)
	v_mfma_f32_32x32x16_bf16 v[64:79], v[152:155], v[102:105], v[64:79]
	ds_read_b128 v[152:155], v173 offset:45184
	s_waitcnt lgkmcnt(1)
	v_mfma_f32_32x32x16_bf16 v[80:95], v[148:151], v[102:105], v[80:95]
	ds_read_b128 v[148:151], v173 offset:32896
	s_waitcnt lgkmcnt(1)
	v_mfma_f32_32x32x16_bf16 v[64:79], v[152:155], v[98:101], v[64:79]
	s_waitcnt lgkmcnt(0)
	v_mfma_f32_32x32x16_bf16 v[80:95], v[148:151], v[98:101], v[80:95]
	ds_read_b128 v[148:151], v184 offset:33024
	ds_read_b128 v[152:155], v184 offset:45312
	ds_read_b128 v[218:221], v181
	s_waitcnt lgkmcnt(0)
	v_mfma_f32_32x32x16_bf16 v[64:79], v[152:155], v[218:221], v[64:79]
	v_mfma_f32_32x32x16_bf16 v[80:95], v[148:151], v[218:221], v[80:95]
	ds_read_b128 v[148:151], v192 offset:33024
	ds_read_b128 v[152:155], v192 offset:45312
	ds_read_b128 v[218:221], v181 offset:8192
	s_waitcnt lgkmcnt(0)
	v_mfma_f32_32x32x16_bf16 v[64:79], v[152:155], v[218:221], v[64:79]
	v_mfma_f32_32x32x16_bf16 v[80:95], v[148:151], v[218:221], v[80:95]
	ds_read_b128 v[148:151], v190 offset:33024
	ds_read_b128 v[152:155], v190 offset:45312
	ds_read_b128 v[218:221], v181 offset:16384
	s_waitcnt lgkmcnt(0)
	v_mfma_f32_32x32x16_bf16 v[64:79], v[152:155], v[218:221], v[64:79]
	v_mfma_f32_32x32x16_bf16 v[80:95], v[148:151], v[218:221], v[80:95]
	ds_read_b128 v[148:151], v173 offset:33024
	ds_read_b128 v[152:155], v173 offset:45312
	ds_read_b128 v[218:221], v181 offset:24576
	s_waitcnt lgkmcnt(0)
	v_mfma_f32_32x32x16_bf16 v[64:79], v[152:155], v[218:221], v[64:79]
	v_add_f32_e32 v154, 0, v130
	v_add_f32_e32 v154, v211, v154
	v_add_f32_e32 v154, v131, v154
	v_add_f32_e32 v154, v212, v154
	v_add_f32_e32 v154, v132, v154
	v_add_f32_e32 v154, v213, v154
	v_add_f32_e32 v154, v133, v154
	v_add_f32_e32 v154, v224, v154
	v_add_f32_e32 v154, v137, v154
	v_add_f32_e32 v154, v228, v154
	v_add_f32_e32 v154, v136, v154
	v_add_f32_e32 v154, v229, v154
	v_add_f32_e32 v154, v135, v154
	v_add_f32_e32 v154, v230, v154
	v_add_f32_e32 v154, v134, v154
	v_mfma_f32_32x32x16_bf16 v[80:95], v[148:151], v[218:221], v[80:95]
	v_exp_f32_e32 v148, v156
	v_add_f32_e32 v154, v231, v154
	v_add_f32_e32 v154, v145, v154
	v_exp_f32_e32 v149, v157
	v_add_f32_e32 v154, v147, v154
	v_add_f32_e32 v154, v144, v154
	v_exp_f32_e32 v150, v191
	v_add_f32_e32 v154, v148, v154
	v_add_f32_e32 v154, v143, v154
	v_exp_f32_e32 v151, v205
	v_add_f32_e32 v154, v149, v154
	v_add_f32_e32 v154, v140, v154
	v_exp_f32_e32 v152, v207
	v_add_f32_e32 v154, v150, v154
	v_add_f32_e32 v154, v139, v154
	v_exp_f32_e32 v153, v210
	v_add_f32_e32 v154, v151, v154
	v_add_f32_e32 v154, v146, v154
	v_add_f32_e32 v154, v152, v154
	v_add_f32_e32 v154, v142, v154
	v_add_f32_e32 v154, v153, v154
	v_add_f32_e32 v154, v141, v154
	v_add_f32_e32 v226, v138, v154
	v_mov_b32_e32 v227, v226
	v_cvt_pk_bf16_f32 v130, v130, v211
	v_cvt_pk_bf16_f32 v131, v131, v212
	v_cvt_pk_bf16_f32 v132, v132, v213
	s_nop 1
	v_permlane32_swap_b32_e32 v226, v227
	v_cvt_pk_bf16_f32 v133, v133, v224
	v_permlane32_swap_b32_e32 v130, v132
	v_cvt_pk_bf16_f32 v154, v137, v228
	v_cvt_pk_bf16_f32 v155, v136, v229
	v_cvt_pk_bf16_f32 v156, v135, v230
	v_cvt_pk_bf16_f32 v157, v134, v231
	v_cvt_pk_bf16_f32 v218, v145, v147
	v_cvt_pk_bf16_f32 v219, v144, v148
	v_cvt_pk_bf16_f32 v220, v143, v149
	v_cvt_pk_bf16_f32 v221, v140, v150
	v_cvt_pk_bf16_f32 v228, v139, v151
	v_cvt_pk_bf16_f32 v229, v146, v152
	v_cvt_pk_bf16_f32 v230, v142, v153
	v_cvt_pk_bf16_f32 v231, v141, v138
	v_permlane32_swap_b32_e32 v131, v133
	v_permlane32_swap_b32_e32 v154, v156
	v_permlane32_swap_b32_e32 v155, v157
	v_permlane32_swap_b32_e32 v218, v220
	v_permlane32_swap_b32_e32 v219, v221
	v_permlane32_swap_b32_e32 v228, v230
	v_permlane32_swap_b32_e32 v229, v231
	s_add_i32 s38, s69, 1
	s_cmp_lt_u32 s38, s68
	s_cselect_b32 s14, 0, s68
	s_cselect_b32 s15, s25, s28
	s_lshl_b32 s14, s14, 6
	s_sub_i32 s14, s15, s14
	s_add_i32 s14, s37, s14
	s_add_i32 s14, s14, 64
	s_ashr_i32 s15, s14, 31
	v_lshl_add_u64 v[134:135], s[14:15], 0, v[174:175]
	v_lshl_add_u64 v[136:137], v[176:177], 0, s[14:15]
	v_lshlrev_b64 v[134:135], 12, v[134:135]
	v_lshlrev_b64 v[136:137], 12, v[136:137]
	v_lshl_add_u64 v[134:135], v[178:179], 0, v[134:135]
	v_lshl_add_u64 v[138:139], v[178:179], 0, v[136:137]
	v_mad_i64_i32 v[142:143], s[20:21], v164, s14, 0
	v_mad_i64_i32 v[146:147], s[20:21], v168, s14, 0
	v_mad_i64_i32 v[150:151], s[14:15], v172, s14, 0
	global_load_dwordx4 v[134:137], v[134:135], off offset:256
	s_nop 0
	global_load_dwordx4 v[138:141], v[138:139], off offset:256
	v_lshl_add_u64 v[142:143], v[142:143], 1, v[162:163]
	v_lshl_add_u64 v[146:147], v[146:147], 1, v[166:167]
	v_lshl_add_u64 v[150:151], v[150:151], 1, v[170:171]
	global_load_dwordx4 v[142:145], v[142:143], off
	s_nop 0
	global_load_dwordx4 v[146:149], v[146:147], off
	s_nop 0
	global_load_dwordx4 v[150:153], v[150:151], off
	ds_read_b64_tr_b16 v[232:233], v169 offset:0
	ds_read_b64_tr_b16 v[234:235], v169 offset:0x800
	ds_read_b64_tr_b16 v[236:237], v169 offset:0x1000
	ds_read_b64_tr_b16 v[238:239], v169 offset:0x1800
	ds_read_b64_tr_b16 v[240:241], v169 offset:0x2000
	ds_read_b64_tr_b16 v[242:243], v169 offset:0x2800
	ds_read_b64_tr_b16 v[244:245], v169 offset:0x3000
	ds_read_b64_tr_b16 v[246:247], v169 offset:0x3800
	s_waitcnt lgkmcnt(0)
; #define SBAR() __builtin_amdgcn_sched_barrier(0)
; template <int OFF> __device__ __forceinline__ s16x4 tr_read(int vb) { s16x4 r; asm volatile("ds_read_b64_tr_b16 %0, %1 offset:%2" : "=&v"(r) : "v"(vb), "i"(OFF) : "memory"); return r; }
; template <int D0> __device__ __forceinline__ void pv_one(f32x16& od, int vb, bf16x8 pa0, bf16x8 pa1, bf16x8 pa2, bf16x8 pa3) {
;     const s16x4 l0 = tr_read<v_rd_off(D0, 0, 0)>(vb), h0 = tr_read<v_rd_off(D0, 0, 1)>(vb), l1 = tr_read<v_rd_off(D0, 1, 0)>(vb), h1 = tr_read<v_rd_off(D0, 1, 1)>(vb);
;     const s16x4 l2 = tr_read<v_rd_off(D0, 2, 0)>(vb), h2 = tr_read<v_rd_off(D0, 2, 1)>(vb), l3 = tr_read<v_rd_off(D0, 3, 0)>(vb), h3 = tr_read<v_rd_off(D0, 3, 1)>(vb);
;     asm volatile("s_waitcnt lgkmcnt(0)" ::: "memory"); SBAR();
;     ...
;     od = __builtin_amdgcn_mfma_f32_32x32x16_bf16(pa0, PK(l0, h0), od, 0, 0, 0);
;     od = __builtin_amdgcn_mfma_f32_32x32x16_bf16(pa1, PK(l1, h1), od, 0, 0, 0);
;     od = __builtin_amdgcn_mfma_f32_32x32x16_bf16(pa2, PK(l2, h2), od, 0, 0, 0);
;     od = __builtin_amdgcn_mfma_f32_32x32x16_bf16(pa3, PK(l3, h3), od, 0, 0, 0);
;     ...
; }
; __device__ __forceinline__ void pv_d0(f32x16* o, int vb, bf16x8 pa0, bf16x8 pa1, bf16x8 pa2, bf16x8 pa3) {
;     pv_one<0>(o[0], vb, pa0, pa1, pa2, pa3); pv_one<1>(o[1], vb, pa0, pa1, pa2, pa3); pv_one<2>(o[2], vb, pa0, pa1, pa2, pa3); pv_one<3>(o[3], vb, pa0, pa1, pa2, pa3);
; }
; __device__ __forceinline__ void partialSM(f32x16& p0, f32x16& p1, float& m_reg, float& mn, float& alpha, const float C, const float thr) {
;     float pmax = p0[0];
; #pragma unroll
;     for (int r = 1; r < 16; ++r) pmax = fmaxf(pmax, p0[r]);
; #pragma unroll
;     for (int r = 0; r < 16; ++r) pmax = fmaxf(pmax, p1[r]);
;     { auto rr = __builtin_amdgcn_permlane32_swap(__float_as_uint(pmax), __float_as_uint(pmax), false, false);
;       pmax = fmaxf(__uint_as_float(rr[0]), __uint_as_float(rr[1])); }
;     if (__builtin_expect(__all(pmax - m_reg <= thr), 1)) { mn = m_reg; alpha = 1.f; }
;     else { mn = fmaxf(m_reg, pmax); alpha = __builtin_amdgcn_exp2f((m_reg - mn) * C); m_reg = mn; }
;     const float mnC = -mn * C;
; #pragma unroll
;     for (int r = 0; r < 16; ++r) p0[r] = fmaf(p0[r], C, mnC);
; #pragma unroll
	s_nop 0
	v_mfma_f32_32x32x16_bf16 v[48:63], v[130:133], v[232:235], v[48:63]
	ds_read_b64_tr_b16 v[232:233], v169 offset:0x200
	ds_read_b64_tr_b16 v[234:235], v169 offset:0xa00
	v_mfma_f32_32x32x16_bf16 v[48:63], v[154:157], v[236:239], v[48:63]
	ds_read_b64_tr_b16 v[236:237], v169 offset:0x1200
	ds_read_b64_tr_b16 v[238:239], v169 offset:0x1a00
	v_mfma_f32_32x32x16_bf16 v[48:63], v[218:221], v[240:243], v[48:63]
	ds_read_b64_tr_b16 v[240:241], v169 offset:0x2200
	ds_read_b64_tr_b16 v[242:243], v169 offset:0x2a00
	v_mfma_f32_32x32x16_bf16 v[48:63], v[228:231], v[244:247], v[48:63]
	ds_read_b64_tr_b16 v[244:245], v169 offset:0x3200
	ds_read_b64_tr_b16 v[246:247], v169 offset:0x3a00
	s_waitcnt lgkmcnt(6)
	v_mfma_f32_32x32x16_bf16 v[32:47], v[130:133], v[232:235], v[32:47]
	ds_read_b64_tr_b16 v[232:233], v169 offset:0x400
	ds_read_b64_tr_b16 v[234:235], v169 offset:0xc00
	s_waitcnt lgkmcnt(6)
	v_mfma_f32_32x32x16_bf16 v[32:47], v[154:157], v[236:239], v[32:47]
	ds_read_b64_tr_b16 v[236:237], v169 offset:0x1400
	ds_read_b64_tr_b16 v[238:239], v169 offset:0x1c00
	s_waitcnt lgkmcnt(6)
	v_mfma_f32_32x32x16_bf16 v[32:47], v[218:221], v[240:243], v[32:47]
	ds_read_b64_tr_b16 v[240:241], v169 offset:0x2400
	ds_read_b64_tr_b16 v[242:243], v169 offset:0x2c00
	s_waitcnt lgkmcnt(6)
	v_mfma_f32_32x32x16_bf16 v[32:47], v[228:231], v[244:247], v[32:47]
	ds_read_b64_tr_b16 v[244:245], v169 offset:0x3400
	ds_read_b64_tr_b16 v[246:247], v169 offset:0x3c00
	s_waitcnt lgkmcnt(6)
	v_mfma_f32_32x32x16_bf16 v[16:31], v[130:133], v[232:235], v[16:31]
	ds_read_b64_tr_b16 v[232:233], v169 offset:0x600
	ds_read_b64_tr_b16 v[234:235], v169 offset:0xe00
	s_waitcnt lgkmcnt(6)
	v_mfma_f32_32x32x16_bf16 v[16:31], v[154:157], v[236:239], v[16:31]
	ds_read_b64_tr_b16 v[236:237], v169 offset:0x1600
	ds_read_b64_tr_b16 v[238:239], v169 offset:0x1e00
	s_waitcnt lgkmcnt(6)
	v_mfma_f32_32x32x16_bf16 v[16:31], v[218:221], v[240:243], v[16:31]
	ds_read_b64_tr_b16 v[240:241], v169 offset:0x2600
	ds_read_b64_tr_b16 v[242:243], v169 offset:0x2e00
	s_waitcnt lgkmcnt(6)
	v_mfma_f32_32x32x16_bf16 v[16:31], v[228:231], v[244:247], v[16:31]
	ds_read_b64_tr_b16 v[244:245], v169 offset:0x3600
	ds_read_b64_tr_b16 v[246:247], v169 offset:0x3e00
	s_waitcnt lgkmcnt(6)
	v_mfma_f32_32x32x16_bf16 v[0:15], v[130:133], v[232:235], v[0:15]
	v_max_f32_e32 v130, v81, v81
	v_max_f32_e32 v131, v80, v80
	v_max_f32_e32 v130, v131, v130
	v_max3_f32 v130, v130, v82, v83
	v_max3_f32 v130, v130, v84, v85
	v_max3_f32 v130, v130, v86, v87
	v_max3_f32 v130, v130, v88, v89
	v_max3_f32 v130, v130, v90, v91
	v_max3_f32 v130, v130, v92, v93
	s_waitcnt lgkmcnt(4)
	v_mfma_f32_32x32x16_bf16 v[0:15], v[154:157], v[236:239], v[0:15]
	v_max3_f32 v130, v130, v94, v95
	v_max3_f32 v130, v130, v64, v65
	v_max3_f32 v130, v130, v66, v67
	v_max3_f32 v130, v130, v68, v69
	v_max3_f32 v130, v130, v70, v71
	v_max3_f32 v130, v130, v72, v73
	v_max3_f32 v130, v130, v74, v75
	v_max3_f32 v130, v130, v76, v77
	s_waitcnt lgkmcnt(2)
	v_mfma_f32_32x32x16_bf16 v[0:15], v[218:221], v[240:243], v[0:15]
	v_max3_f32 v130, v130, v78, v79
	v_mov_b32_e32 v131, v130
	s_nop 1
	v_permlane32_swap_b32_e32 v130, v131
	v_max_f32_e32 v131, v131, v131
	v_max_f32_e32 v130, v130, v130
	v_max_f32_e32 v130, v130, v131
	v_sub_f32_e32 v131, v130, v204
	v_cmp_ge_f32_e32 vcc, s72, v131
	v_max_f32_e32 v131, v204, v204
	v_max_f32_e32 v130, v131, v130
	s_waitcnt lgkmcnt(0)
	v_mfma_f32_32x32x16_bf16 v[0:15], v[228:231], v[244:247], v[0:15]
	v_sub_f32_e32 v131, v204, v130
	v_mul_f32_e32 v131, 0x3dd53b94, v131
	v_exp_f32_e32 v131, v131
	s_cmp_eq_u64 vcc, exec
	s_cselect_b64 s[14:15], -1, 0
	v_cndmask_b32_e64 v224, v131, 1.0, s[14:15]
	v_cmp_gt_f32_e32 vcc, 1.0, v224
	s_barrier
	s_waitcnt vmcnt(4)
	ds_write_b128 v186, v[134:137] offset:16384
	s_waitcnt vmcnt(3)
	ds_write_b128 v188, v[138:141] offset:16384
	s_waitcnt vmcnt(2)
	ds_write_b128 v194, v[142:145] offset:57344
	s_waitcnt vmcnt(1)
	ds_write_b128 v196, v[146:149] offset:57344
	s_waitcnt vmcnt(0)
	ds_write_b128 v198, v[150:153] offset:57344
	s_cbranch_vccz .LBB0_227
	s_and_saveexec_b64 s[20:21], s[12:13]
	ds_write_b32 v165, v224 offset:128
	s_or_b64 exec, exec, s[20:21]
	s_waitcnt lgkmcnt(0)
	v_add_u32_e32 v131, v161, v96
	ds_read_b128 v[132:135], v131 offset:224
	ds_read_b128 v[136:139], v131 offset:192
	ds_read_b128 v[140:143], v131 offset:160
	ds_read_b128 v[144:147], v131 offset:128
	s_waitcnt lgkmcnt(3)
	v_pk_mul_f32 v[60:61], v[60:61], v[132:133]
	s_waitcnt lgkmcnt(2)
	v_pk_mul_f32 v[56:57], v[56:57], v[136:137]
	s_waitcnt lgkmcnt(1)
	v_pk_mul_f32 v[52:53], v[52:53], v[140:141]
	v_pk_mul_f32 v[62:63], v[62:63], v[134:135]
	v_pk_mul_f32 v[58:59], v[58:59], v[138:139]
	v_pk_mul_f32 v[54:55], v[54:55], v[142:143]
	s_waitcnt lgkmcnt(0)
	v_pk_mul_f32 v[50:51], v[50:51], v[146:147]
	v_pk_mul_f32 v[48:49], v[48:49], v[144:145]
	v_pk_mul_f32 v[44:45], v[44:45], v[132:133]
	v_pk_mul_f32 v[40:41], v[40:41], v[136:137]
	v_pk_mul_f32 v[36:37], v[36:37], v[140:141]
	v_pk_mul_f32 v[46:47], v[46:47], v[134:135]
	v_pk_mul_f32 v[42:43], v[42:43], v[138:139]
	v_pk_mul_f32 v[38:39], v[38:39], v[142:143]
	v_pk_mul_f32 v[34:35], v[34:35], v[146:147]
	v_pk_mul_f32 v[32:33], v[32:33], v[144:145]
	v_pk_mul_f32 v[28:29], v[28:29], v[132:133]
	v_pk_mul_f32 v[24:25], v[24:25], v[136:137]
	v_pk_mul_f32 v[20:21], v[20:21], v[140:141]
	v_pk_mul_f32 v[30:31], v[30:31], v[134:135]
	v_pk_mul_f32 v[26:27], v[26:27], v[138:139]
	v_pk_mul_f32 v[22:23], v[22:23], v[142:143]
	v_pk_mul_f32 v[18:19], v[18:19], v[146:147]
	v_pk_mul_f32 v[16:17], v[16:17], v[144:145]
	v_pk_mul_f32 v[12:13], v[12:13], v[132:133]
	v_pk_mul_f32 v[8:9], v[8:9], v[136:137]
	v_pk_mul_f32 v[4:5], v[4:5], v[140:141]
	v_pk_mul_f32 v[14:15], v[14:15], v[134:135]
	v_pk_mul_f32 v[10:11], v[10:11], v[138:139]
	v_pk_mul_f32 v[6:7], v[6:7], v[142:143]
	v_pk_mul_f32 v[2:3], v[2:3], v[146:147]
	v_pk_mul_f32 v[0:1], v[0:1], v[144:145]
